# speedup vs baseline: 1.0088x; 1.0088x over previous
; #define PG8_STAGE(bufoff, gbase, voff) do { _Pragma("unroll") for (int _i = 0; _i < 2; ++_i) \
;         __builtin_amdgcn_global_load_lds((const unsigned*)((const char*)(gbase) + (voff)[_i]), (LAS unsigned*)(lds + (bufoff) + ldsw + _i * 8192), 16, 0, 0); } while (0)
; #define PG8_LDA(dst, b, h) do { _Pragma("unroll") for (int m = 0; m < 4; ++m) _Pragma("unroll") for (int k = 0; k < 2; ++k) dst[m][k] = *(const LAS bf16x8*)(lds + PG8_SA(b, h) + aoff + m * 2048 + k * 1024); } while (0)
; #define PG8_LDB(dst, b, h) do { _Pragma("unroll") for (int n = 0; n < 2; ++n) _Pragma("unroll") for (int k = 0; k < 2; ++k) dst[n][k] = *(const LAS bf16x8*)(lds + PG8_SB(b, h) + boff + n * 2048 + k * 1024); } while (0)
; #define PG8_WAIT_V(n) asm volatile("s_waitcnt vmcnt(" #n ")" ::: "memory")
; #define PG8_WAIT_L(n) asm volatile("s_waitcnt lgkmcnt(" #n ")" ::: "memory")
; #define PG8_BAR __builtin_amdgcn_s_barrier()
; #define PG8_SCHED __builtin_amdgcn_sched_barrier(0)
; template <class Epi, class Sched, bool FUSED = false, bool APERM = false>
; __device__ __forceinline__ void gemm_phase(int wid_s, LAS unsigned char* lds, const Gemm g, const Sched& S, const Epi& E) {
;     ...
;             const bool last = (t == nt - 2);
;             const char* a1 = cA + (size_t)(t + 1) * kstep;
;             const char* a2 = last ? nA : cA + (size_t)(t + 2) * kstep; const char* b2 = last ? nB : cB + (size_t)(t + 2) * kstep;
;             const char* a3 = a2 + kstep; const char* b3 = b2 + kstep;
;             if (last && has_next) S.a_ready(nxt);
;             PG8_LDB(B0, 0, 0); PG8_LDB(B1, 0, 1); PG8_SCHED; PG8_LDA(At, 0, 0); PG8_STAGE(PG8_SA(1, 1), a1 + hstep, voffA);
;             PG8_WAIT_V(8); PG8_WAIT_L(0); PG8_BAR; PG8_MMA(0, 0, At, B0); PG8_MMA(0, 1, At, B1); PG8_BAR; PG8_SCHED;
;             PG8_LDA(At, 0, 1); PG8_STAGE(PG8_SB(0, 0), b2, voffB); PG8_STAGE(PG8_SB(0, 1), b2 + hstep, voffB); PG8_STAGE(PG8_SA(0, 0), a2, voffA);
;             PG8_WAIT_V(8); PG8_WAIT_L(0); PG8_BAR; PG8_MMA(1, 0, At, B0); PG8_MMA(1, 1, At, B1); PG8_BAR; PG8_SCHED;
.LBB0_342:
	s_add_u32 s38, s36, 0xfff80080
	s_addc_u32 s39, s37, -1
	s_add_i32 s64, 0, 0x10000
	s_cmp_eq_u32 s63, 28
	s_cselect_b32 s41, s1, s39
	s_cselect_b32 s40, s23, s38
	s_cselect_b32 s39, s25, s62
	s_cselect_b32 s38, s35, s61
	s_add_i32 s66, 0, 0x14000
	v_add_u32_e32 v144, s64, v227
	v_add_u32_e32 v160, s66, v227
	ds_read_b128 v[132:135], v144
	ds_read_b128 v[136:139], v144 offset:1024
	ds_read_b128 v[140:143], v144 offset:2048
	ds_read_b128 v[144:147], v144 offset:3072
	ds_read_b128 v[148:151], v160
	ds_read_b128 v[152:155], v160 offset:1024
	ds_read_b128 v[156:159], v160 offset:2048
	ds_read_b128 v[160:163], v160 offset:3072
	v_lshl_add_u64 v[214:215], s[36:37], 0, v[212:213]
	s_add_i32 m0, s48, 0xc000
	ds_read_b128 v[164:167], v228
	ds_read_b128 v[168:171], v228 offset:1024
	ds_read_b128 v[172:175], v228 offset:2048
	ds_read_b128 v[176:179], v228 offset:3072
	ds_read_b128 v[180:183], v228 offset:4096
	ds_read_b128 v[184:187], v228 offset:5120
	ds_read_b128 v[188:191], v228 offset:6144
	ds_read_b128 v[192:195], v228 offset:7168
	global_load_lds_dwordx4 v[214:215], off
	v_lshl_add_u64 v[214:215], s[36:37], 0, v[210:211]
	s_add_i32 m0, s48, 0xe000
	s_nop 0
	global_load_lds_dwordx4 v[214:215], off
	s_waitcnt vmcnt(8)
	s_waitcnt lgkmcnt(0)
	v_mfma_f32_16x16x32_f16 v[128:131], v[132:135], v[164:167], v[128:131]
	v_mfma_f32_16x16x32_f16 v[124:127], v[140:143], v[164:167], v[124:127]
	v_mfma_f32_16x16x32_f16 v[112:115], v[132:135], v[172:175], v[112:115]
	v_mfma_f32_16x16x32_f16 v[108:111], v[140:143], v[172:175], v[108:111]
	s_barrier
	s_setprio 1
	v_mfma_f32_16x16x32_f16 v[96:99], v[132:135], v[180:183], v[96:99]
	v_mfma_f32_16x16x32_f16 v[92:95], v[140:143], v[180:183], v[92:95]
	v_mfma_f32_16x16x32_f16 v[80:83], v[132:135], v[188:191], v[80:83]
	v_mfma_f32_16x16x32_f16 v[76:79], v[140:143], v[188:191], v[76:79]
	v_mfma_f32_16x16x32_f16 v[128:131], v[136:139], v[168:171], v[128:131]
	v_mfma_f32_16x16x32_f16 v[124:127], v[144:147], v[168:171], v[124:127]
	v_mfma_f32_16x16x32_f16 v[112:115], v[136:139], v[176:179], v[112:115]
	v_mfma_f32_16x16x32_f16 v[108:111], v[144:147], v[176:179], v[108:111]
	v_mfma_f32_16x16x32_f16 v[96:99], v[136:139], v[184:187], v[96:99]
	v_mfma_f32_16x16x32_f16 v[92:95], v[144:147], v[184:187], v[92:95]
	v_mfma_f32_16x16x32_f16 v[80:83], v[136:139], v[192:195], v[80:83]
	v_mfma_f32_16x16x32_f16 v[76:79], v[144:147], v[192:195], v[76:79]
	v_mfma_f32_16x16x32_f16 v[120:123], v[148:151], v[164:167], v[120:123]
	v_mfma_f32_16x16x32_f16 v[116:119], v[156:159], v[164:167], v[116:119]
	v_mfma_f32_16x16x32_f16 v[104:107], v[148:151], v[172:175], v[104:107]
	v_mfma_f32_16x16x32_f16 v[100:103], v[156:159], v[172:175], v[100:103]
	v_mfma_f32_16x16x32_f16 v[88:91], v[148:151], v[180:183], v[88:91]
	v_mfma_f32_16x16x32_f16 v[84:87], v[156:159], v[180:183], v[84:87]
	v_mfma_f32_16x16x32_f16 v[68:71], v[148:151], v[188:191], v[68:71]
	v_mfma_f32_16x16x32_f16 v[72:75], v[156:159], v[188:191], v[72:75]
	v_mfma_f32_16x16x32_f16 v[120:123], v[152:155], v[168:171], v[120:123]
	v_mfma_f32_16x16x32_f16 v[116:119], v[160:163], v[168:171], v[116:119]
	v_mfma_f32_16x16x32_f16 v[104:107], v[152:155], v[176:179], v[104:107]
	v_mfma_f32_16x16x32_f16 v[100:103], v[160:163], v[176:179], v[100:103]
	v_mfma_f32_16x16x32_f16 v[88:91], v[152:155], v[184:187], v[88:91]
	v_mfma_f32_16x16x32_f16 v[84:87], v[160:163], v[184:187], v[84:87]
	v_mfma_f32_16x16x32_f16 v[68:71], v[152:155], v[192:195], v[68:71]
	v_mfma_f32_16x16x32_f16 v[72:75], v[160:163], v[192:195], v[72:75]
	s_setprio 0
	s_barrier
	s_add_i32 s64, s64, s47
	v_lshl_add_u64 v[214:215], s[38:39], 0, v[0:1]
	s_mov_b32 m0, s64
	ds_read_b128 v[164:167], v228 offset:16384
	ds_read_b128 v[168:171], v228 offset:17408
	ds_read_b128 v[172:175], v228 offset:18432
	ds_read_b128 v[176:179], v228 offset:19456
	ds_read_b128 v[180:183], v228 offset:20480
	ds_read_b128 v[184:187], v228 offset:21504
	ds_read_b128 v[188:191], v228 offset:22528
	ds_read_b128 v[192:195], v228 offset:23552
	global_load_lds_dwordx4 v[214:215], off
	s_add_i32 m0, s64, 0x2000
	s_add_u32 s64, s38, 0x80000
	v_lshl_add_u64 v[216:217], s[38:39], 0, v[208:209]
	s_addc_u32 s65, s39, 0
	s_add_i32 s66, s66, s47
	global_load_lds_dwordx4 v[216:217], off
	v_lshl_add_u64 v[218:219], s[64:65], 0, v[0:1]
	s_mov_b32 m0, s66
	v_lshl_add_u64 v[220:221], s[40:41], 0, v[208:209]
	global_load_lds_dwordx4 v[218:219], off
	v_lshl_add_u64 v[218:219], s[64:65], 0, v[208:209]
	s_add_i32 m0, s66, 0x2000
	s_nop 0
	global_load_lds_dwordx4 v[218:219], off
	v_lshl_add_u64 v[218:219], s[40:41], 0, v[0:1]
	s_mov_b32 m0, s48
	s_nop 0
	global_load_lds_dwordx4 v[218:219], off
	s_mov_b32 m0, s49
	s_nop 0
	global_load_lds_dwordx4 v[220:221], off
	s_waitcnt vmcnt(8)
	s_waitcnt lgkmcnt(0)
	v_mfma_f32_16x16x32_f16 v[64:67], v[132:135], v[164:167], v[64:67]
	v_mfma_f32_16x16x32_f16 v[60:63], v[140:143], v[164:167], v[60:63]
	v_mfma_f32_16x16x32_f16 v[48:51], v[132:135], v[172:175], v[48:51]
	v_mfma_f32_16x16x32_f16 v[44:47], v[140:143], v[172:175], v[44:47]
	s_barrier
; #define PG8_STAGE(bufoff, gbase, voff) do { _Pragma("unroll") for (int _i = 0; _i < 2; ++_i) \
;         __builtin_amdgcn_global_load_lds((const unsigned*)((const char*)(gbase) + (voff)[_i]), (LAS unsigned*)(lds + (bufoff) + ldsw + _i * 8192), 16, 0, 0); } while (0)
; #define PG8_LDA(dst, b, h) do { _Pragma("unroll") for (int m = 0; m < 4; ++m) _Pragma("unroll") for (int k = 0; k < 2; ++k) dst[m][k] = *(const LAS bf16x8*)(lds + PG8_SA(b, h) + aoff + m * 2048 + k * 1024); } while (0)
; #define PG8_LDB(dst, b, h) do { _Pragma("unroll") for (int n = 0; n < 2; ++n) _Pragma("unroll") for (int k = 0; k < 2; ++k) dst[n][k] = *(const LAS bf16x8*)(lds + PG8_SB(b, h) + boff + n * 2048 + k * 1024); } while (0)
; #define PG8_WAIT_V(n) asm volatile("s_waitcnt vmcnt(" #n ")" ::: "memory")
; #define PG8_WAIT_L(n) asm volatile("s_waitcnt lgkmcnt(" #n ")" ::: "memory")
; #define PG8_BAR __builtin_amdgcn_s_barrier()
; #define PG8_SCHED __builtin_amdgcn_sched_barrier(0)
; template <class Epi, class Sched, bool FUSED = false, bool APERM = false>
; __device__ __forceinline__ void gemm_phase(int wid_s, LAS unsigned char* lds, const Gemm g, const Sched& S, const Epi& E) {
;     ...
;             PG8_WAIT_V(8); PG8_WAIT_L(0); PG8_BAR; PG8_MMA(1, 0, At, B0); PG8_MMA(1, 1, At, B1); PG8_BAR; PG8_SCHED;
;             PG8_LDB(B0, 1, 0); PG8_LDB(B1, 1, 1); PG8_SCHED; PG8_LDA(At, 1, 0); PG8_STAGE(PG8_SA(0, 1), a2 + hstep, voffA);
;             PG8_WAIT_V(8); PG8_WAIT_L(0); PG8_BAR; PG8_MMA(0, 0, At, B0); PG8_MMA(0, 1, At, B1); PG8_BAR; PG8_SCHED;
	s_setprio 1
	v_mfma_f32_16x16x32_f16 v[32:35], v[132:135], v[180:183], v[32:35]
	v_mfma_f32_16x16x32_f16 v[28:31], v[140:143], v[180:183], v[28:31]
	v_mfma_f32_16x16x32_f16 v[12:15], v[132:135], v[188:191], v[12:15]
	v_mfma_f32_16x16x32_f16 v[16:19], v[140:143], v[188:191], v[16:19]
	v_mfma_f32_16x16x32_f16 v[64:67], v[136:139], v[168:171], v[64:67]
	v_mfma_f32_16x16x32_f16 v[60:63], v[144:147], v[168:171], v[60:63]
	v_mfma_f32_16x16x32_f16 v[48:51], v[136:139], v[176:179], v[48:51]
	v_mfma_f32_16x16x32_f16 v[44:47], v[144:147], v[176:179], v[44:47]
	v_mfma_f32_16x16x32_f16 v[32:35], v[136:139], v[184:187], v[32:35]
	v_mfma_f32_16x16x32_f16 v[28:31], v[144:147], v[184:187], v[28:31]
	v_mfma_f32_16x16x32_f16 v[12:15], v[136:139], v[192:195], v[12:15]
	v_mfma_f32_16x16x32_f16 v[16:19], v[144:147], v[192:195], v[16:19]
	v_mfma_f32_16x16x32_f16 v[56:59], v[148:151], v[164:167], v[56:59]
	v_mfma_f32_16x16x32_f16 v[52:55], v[156:159], v[164:167], v[52:55]
	v_mfma_f32_16x16x32_f16 v[40:43], v[148:151], v[172:175], v[40:43]
	v_mfma_f32_16x16x32_f16 v[36:39], v[156:159], v[172:175], v[36:39]
	v_mfma_f32_16x16x32_f16 v[24:27], v[148:151], v[180:183], v[24:27]
	v_mfma_f32_16x16x32_f16 v[20:23], v[156:159], v[180:183], v[20:23]
	v_mfma_f32_16x16x32_f16 v[4:7], v[148:151], v[188:191], v[4:7]
	v_mfma_f32_16x16x32_f16 v[8:11], v[156:159], v[188:191], v[8:11]
	v_mfma_f32_16x16x32_f16 v[56:59], v[152:155], v[168:171], v[56:59]
	v_mfma_f32_16x16x32_f16 v[52:55], v[160:163], v[168:171], v[52:55]
	v_mfma_f32_16x16x32_f16 v[40:43], v[152:155], v[176:179], v[40:43]
	v_mfma_f32_16x16x32_f16 v[36:39], v[160:163], v[176:179], v[36:39]
	v_mfma_f32_16x16x32_f16 v[24:27], v[152:155], v[184:187], v[24:27]
	v_mfma_f32_16x16x32_f16 v[20:23], v[160:163], v[184:187], v[20:23]
	v_mfma_f32_16x16x32_f16 v[4:7], v[152:155], v[192:195], v[4:7]
	v_mfma_f32_16x16x32_f16 v[8:11], v[160:163], v[192:195], v[8:11]
	s_setprio 0
	s_barrier
	s_add_i32 s64, 0, 0x18000
	s_add_i32 s65, 0, 0x1c000
	v_add_u32_e32 v144, s64, v227
	v_add_u32_e32 v160, s65, v227
	ds_read_b128 v[132:135], v144
	ds_read_b128 v[136:139], v144 offset:1024
	ds_read_b128 v[140:143], v144 offset:2048
	ds_read_b128 v[144:147], v144 offset:3072
	ds_read_b128 v[148:151], v160
	ds_read_b128 v[152:155], v160 offset:1024
	ds_read_b128 v[156:159], v160 offset:2048
	ds_read_b128 v[160:163], v160 offset:3072
	s_add_u32 s40, s40, 0x80000
	s_addc_u32 s41, s41, 0
	s_mov_b32 m0, s50
	v_lshl_add_u64 v[222:223], s[40:41], 0, v[0:1]
	ds_read_b128 v[164:167], v228 offset:32768
	ds_read_b128 v[168:171], v228 offset:33792
	ds_read_b128 v[172:175], v228 offset:34816
	ds_read_b128 v[176:179], v228 offset:35840
	ds_read_b128 v[180:183], v228 offset:36864
	ds_read_b128 v[184:187], v228 offset:37888
	ds_read_b128 v[188:191], v228 offset:38912
	ds_read_b128 v[192:195], v228 offset:39936
	global_load_lds_dwordx4 v[222:223], off
	v_lshl_add_u64 v[222:223], s[40:41], 0, v[208:209]
	s_mov_b32 m0, s51
	s_nop 0
	global_load_lds_dwordx4 v[222:223], off
	s_waitcnt vmcnt(8)
	s_waitcnt lgkmcnt(0)
	v_mfma_f32_16x16x32_f16 v[128:131], v[132:135], v[164:167], v[128:131]
	v_mfma_f32_16x16x32_f16 v[124:127], v[140:143], v[164:167], v[124:127]
	v_mfma_f32_16x16x32_f16 v[112:115], v[132:135], v[172:175], v[112:115]
	v_mfma_f32_16x16x32_f16 v[108:111], v[140:143], v[172:175], v[108:111]
	s_barrier
	s_setprio 1
	v_mfma_f32_16x16x32_f16 v[96:99], v[132:135], v[180:183], v[96:99]
	v_mfma_f32_16x16x32_f16 v[92:95], v[140:143], v[180:183], v[92:95]
	v_mfma_f32_16x16x32_f16 v[80:83], v[132:135], v[188:191], v[80:83]
	v_mfma_f32_16x16x32_f16 v[76:79], v[140:143], v[188:191], v[76:79]
	v_mfma_f32_16x16x32_f16 v[128:131], v[136:139], v[168:171], v[128:131]
	v_mfma_f32_16x16x32_f16 v[124:127], v[144:147], v[168:171], v[124:127]
	v_mfma_f32_16x16x32_f16 v[112:115], v[136:139], v[176:179], v[112:115]
	v_mfma_f32_16x16x32_f16 v[108:111], v[144:147], v[176:179], v[108:111]
	v_mfma_f32_16x16x32_f16 v[96:99], v[136:139], v[184:187], v[96:99]
	v_mfma_f32_16x16x32_f16 v[92:95], v[144:147], v[184:187], v[92:95]
	v_mfma_f32_16x16x32_f16 v[80:83], v[136:139], v[192:195], v[80:83]
	v_mfma_f32_16x16x32_f16 v[76:79], v[144:147], v[192:195], v[76:79]
	v_mfma_f32_16x16x32_f16 v[120:123], v[148:151], v[164:167], v[120:123]
	v_mfma_f32_16x16x32_f16 v[116:119], v[156:159], v[164:167], v[116:119]
	v_mfma_f32_16x16x32_f16 v[104:107], v[148:151], v[172:175], v[104:107]
	v_mfma_f32_16x16x32_f16 v[100:103], v[156:159], v[172:175], v[100:103]
	v_mfma_f32_16x16x32_f16 v[88:91], v[148:151], v[180:183], v[88:91]
	v_mfma_f32_16x16x32_f16 v[84:87], v[156:159], v[180:183], v[84:87]
	v_mfma_f32_16x16x32_f16 v[68:71], v[148:151], v[188:191], v[68:71]
	v_mfma_f32_16x16x32_f16 v[72:75], v[156:159], v[188:191], v[72:75]
	v_mfma_f32_16x16x32_f16 v[120:123], v[152:155], v[168:171], v[120:123]
	v_mfma_f32_16x16x32_f16 v[116:119], v[160:163], v[168:171], v[116:119]
	v_mfma_f32_16x16x32_f16 v[104:107], v[152:155], v[176:179], v[104:107]
	v_mfma_f32_16x16x32_f16 v[100:103], v[160:163], v[176:179], v[100:103]
	v_mfma_f32_16x16x32_f16 v[88:91], v[152:155], v[184:187], v[88:91]
	v_mfma_f32_16x16x32_f16 v[84:87], v[160:163], v[184:187], v[84:87]
	v_mfma_f32_16x16x32_f16 v[68:71], v[152:155], v[192:195], v[68:71]
	v_mfma_f32_16x16x32_f16 v[72:75], v[160:163], v[192:195], v[72:75]
	s_setprio 0
	s_barrier
; #define PG8_STAGE(bufoff, gbase, voff) do { _Pragma("unroll") for (int _i = 0; _i < 2; ++_i) \
;         __builtin_amdgcn_global_load_lds((const unsigned*)((const char*)(gbase) + (voff)[_i]), (LAS unsigned*)(lds + (bufoff) + ldsw + _i * 8192), 16, 0, 0); } while (0)
; #define PG8_LDA(dst, b, h) do { _Pragma("unroll") for (int m = 0; m < 4; ++m) _Pragma("unroll") for (int k = 0; k < 2; ++k) dst[m][k] = *(const LAS bf16x8*)(lds + PG8_SA(b, h) + aoff + m * 2048 + k * 1024); } while (0)
; #define PG8_WAIT_V(n) asm volatile("s_waitcnt vmcnt(" #n ")" ::: "memory")
; #define PG8_WAIT_L(n) asm volatile("s_waitcnt lgkmcnt(" #n ")" ::: "memory")
; #define PG8_BAR __builtin_amdgcn_s_barrier()
; #define PG8_SCHED __builtin_amdgcn_sched_barrier(0)
; template <class Epi, class Sched, bool FUSED = false, bool APERM = false>
; __device__ __forceinline__ void gemm_phase(int wid_s, LAS unsigned char* lds, const Gemm g, const Sched& S, const Epi& E) {
;     ...
;             PG8_LDA(At, 1, 1); PG8_STAGE(PG8_SB(1, 0), b3, voffB); PG8_STAGE(PG8_SB(1, 1), b3 + hstep, voffB); PG8_STAGE(PG8_SA(1, 0), a3, voffA);
;             PG8_WAIT_V(8); PG8_WAIT_L(0); PG8_BAR; PG8_MMA(1, 0, At, B0); PG8_MMA(1, 1, At, B1); PG8_BAR; PG8_SCHED;
;         }
;         if (wr == 0) PG8_BAR;
	s_add_i32 s40, s64, s47
	v_lshl_add_u64 v[214:215], v[214:215], 0, s[12:13]
	s_mov_b32 m0, s40
	ds_read_b128 v[164:167], v228 offset:49152
	ds_read_b128 v[168:171], v228 offset:50176
	ds_read_b128 v[172:175], v228 offset:51200
	ds_read_b128 v[176:179], v228 offset:52224
	ds_read_b128 v[180:183], v228 offset:53248
	ds_read_b128 v[184:187], v228 offset:54272
	ds_read_b128 v[188:191], v228 offset:55296
	ds_read_b128 v[192:195], v228 offset:56320
	global_load_lds_dwordx4 v[214:215], off
	s_add_i32 m0, s40, 0x2000
	s_add_u32 s38, s38, 0x80080
	v_lshl_add_u64 v[214:215], v[216:217], 0, s[12:13]
	s_addc_u32 s39, s39, 0
	s_add_i32 s40, s65, s47
	global_load_lds_dwordx4 v[214:215], off
	v_lshl_add_u64 v[214:215], s[38:39], 0, v[0:1]
	s_mov_b32 m0, s40
	s_nop 0
	global_load_lds_dwordx4 v[214:215], off
	v_lshl_add_u64 v[214:215], s[38:39], 0, v[208:209]
	s_add_i32 m0, s40, 0x2000
	s_nop 0
	global_load_lds_dwordx4 v[214:215], off
	v_lshl_add_u64 v[214:215], v[218:219], 0, s[12:13]
	s_mov_b32 m0, s55
	s_nop 0
	global_load_lds_dwordx4 v[214:215], off
	v_lshl_add_u64 v[214:215], v[220:221], 0, s[12:13]
	s_mov_b32 m0, s56
	s_nop 0
	global_load_lds_dwordx4 v[214:215], off
	s_waitcnt vmcnt(8)
	s_waitcnt lgkmcnt(0)
	v_mfma_f32_16x16x32_f16 v[64:67], v[132:135], v[164:167], v[64:67]
	v_mfma_f32_16x16x32_f16 v[60:63], v[140:143], v[164:167], v[60:63]
	v_mfma_f32_16x16x32_f16 v[48:51], v[132:135], v[172:175], v[48:51]
	v_mfma_f32_16x16x32_f16 v[44:47], v[140:143], v[172:175], v[44:47]
	s_barrier
	s_setprio 1
	v_mfma_f32_16x16x32_f16 v[32:35], v[132:135], v[180:183], v[32:35]
	v_mfma_f32_16x16x32_f16 v[28:31], v[140:143], v[180:183], v[28:31]
	v_mfma_f32_16x16x32_f16 v[12:15], v[132:135], v[188:191], v[12:15]
	v_mfma_f32_16x16x32_f16 v[16:19], v[140:143], v[188:191], v[16:19]
	v_mfma_f32_16x16x32_f16 v[64:67], v[136:139], v[168:171], v[64:67]
	v_mfma_f32_16x16x32_f16 v[60:63], v[144:147], v[168:171], v[60:63]
	v_mfma_f32_16x16x32_f16 v[48:51], v[136:139], v[176:179], v[48:51]
	v_mfma_f32_16x16x32_f16 v[44:47], v[144:147], v[176:179], v[44:47]
	v_mfma_f32_16x16x32_f16 v[32:35], v[136:139], v[184:187], v[32:35]
	v_mfma_f32_16x16x32_f16 v[28:31], v[144:147], v[184:187], v[28:31]
	v_mfma_f32_16x16x32_f16 v[12:15], v[136:139], v[192:195], v[12:15]
	v_mfma_f32_16x16x32_f16 v[16:19], v[144:147], v[192:195], v[16:19]
	v_mfma_f32_16x16x32_f16 v[56:59], v[148:151], v[164:167], v[56:59]
	v_mfma_f32_16x16x32_f16 v[52:55], v[156:159], v[164:167], v[52:55]
	v_mfma_f32_16x16x32_f16 v[40:43], v[148:151], v[172:175], v[40:43]
	v_mfma_f32_16x16x32_f16 v[36:39], v[156:159], v[172:175], v[36:39]
	v_mfma_f32_16x16x32_f16 v[24:27], v[148:151], v[180:183], v[24:27]
	v_mfma_f32_16x16x32_f16 v[20:23], v[156:159], v[180:183], v[20:23]
	v_mfma_f32_16x16x32_f16 v[4:7], v[148:151], v[188:191], v[4:7]
	v_mfma_f32_16x16x32_f16 v[8:11], v[156:159], v[188:191], v[8:11]
	v_mfma_f32_16x16x32_f16 v[56:59], v[152:155], v[168:171], v[56:59]
	v_mfma_f32_16x16x32_f16 v[52:55], v[160:163], v[168:171], v[52:55]
	v_mfma_f32_16x16x32_f16 v[40:43], v[152:155], v[176:179], v[40:43]
	v_mfma_f32_16x16x32_f16 v[36:39], v[160:163], v[176:179], v[36:39]
	v_mfma_f32_16x16x32_f16 v[24:27], v[152:155], v[184:187], v[24:27]
	v_mfma_f32_16x16x32_f16 v[20:23], v[160:163], v[184:187], v[20:23]
	v_mfma_f32_16x16x32_f16 v[4:7], v[152:155], v[192:195], v[4:7]
	v_mfma_f32_16x16x32_f16 v[8:11], v[160:163], v[192:195], v[8:11]
	s_setprio 0
	s_barrier
	s_add_i32 s63, s63, 2
	s_add_u32 s61, s61, 0x100
	s_addc_u32 s62, s62, 0
	s_add_u32 s36, s36, 0x100
	s_addc_u32 s37, s37, 0
	s_cmp_gt_u32 s63, 29
	s_cbranch_scc0 .LBB0_342
	s_and_b64 vcc, exec, s[14:15]
	s_cbranch_vccz .LBB0_345
	s_barrier

; #define PG8_STAGE(bufoff, gbase, voff) do { _Pragma("unroll") for (int _i = 0; _i < 2; ++_i) \
;         __builtin_amdgcn_global_load_lds((const unsigned*)((const char*)(gbase) + (voff)[_i]), (LAS unsigned*)(lds + (bufoff) + ldsw + _i * 8192), 16, 0, 0); } while (0)
; #define PG8_LDA(dst, b, h) do { _Pragma("unroll") for (int m = 0; m < 4; ++m) _Pragma("unroll") for (int k = 0; k < 2; ++k) dst[m][k] = *(const LAS bf16x8*)(lds + PG8_SA(b, h) + aoff + m * 2048 + k * 1024); } while (0)
; #define PG8_LDB(dst, b, h) do { _Pragma("unroll") for (int n = 0; n < 2; ++n) _Pragma("unroll") for (int k = 0; k < 2; ++k) dst[n][k] = *(const LAS bf16x8*)(lds + PG8_SB(b, h) + boff + n * 2048 + k * 1024); } while (0)
; #define PG8_WAIT_V(n) asm volatile("s_waitcnt vmcnt(" #n ")" ::: "memory")
; #define PG8_WAIT_L(n) asm volatile("s_waitcnt lgkmcnt(" #n ")" ::: "memory")
; #define PG8_BAR __builtin_amdgcn_s_barrier()
; #define PG8_SCHED __builtin_amdgcn_sched_barrier(0)
; template <class Epi, class Sched, bool FUSED = false, bool APERM = false>
; __device__ __forceinline__ void gemm_phase(int wid_s, LAS unsigned char* lds, const Gemm g, const Sched& S, const Epi& E) {
;     ...
;             const bool last = (t == nt - 2);
;             const char* a1 = cA + (size_t)(t + 1) * kstep;
;             const char* a2 = last ? nA : cA + (size_t)(t + 2) * kstep; const char* b2 = last ? nB : cB + (size_t)(t + 2) * kstep;
;             const char* a3 = a2 + kstep; const char* b3 = b2 + kstep;
;             if (last && has_next) S.a_ready(nxt);
;             PG8_LDB(B0, 0, 0); PG8_LDB(B1, 0, 1); PG8_SCHED; PG8_LDA(At, 0, 0); PG8_STAGE(PG8_SA(1, 1), a1 + hstep, voffA);
;             PG8_WAIT_V(8); PG8_WAIT_L(0); PG8_BAR; PG8_MMA(0, 0, At, B0); PG8_MMA(0, 1, At, B1); PG8_BAR; PG8_SCHED;
;             PG8_LDA(At, 0, 1); PG8_STAGE(PG8_SB(0, 0), b2, voffB); PG8_STAGE(PG8_SB(0, 1), b2 + hstep, voffB); PG8_STAGE(PG8_SA(0, 0), a2, voffA);
;             PG8_WAIT_V(8); PG8_WAIT_L(0); PG8_BAR; PG8_MMA(1, 0, At, B0); PG8_MMA(1, 1, At, B1); PG8_BAR; PG8_SCHED;
.LBB0_582:
	s_add_u32 s24, s22, 0xfffe0080
	s_addc_u32 s25, s23, -1
	s_add_i32 s50, 0, 0x10000
	s_cmp_eq_u32 s49, 4
	s_cselect_b32 s27, s15, s25
	s_cselect_b32 s26, s45, s24
	v_add_u32_e32 v141, s50, v139
	s_cselect_b32 s25, s9, s48
	s_cselect_b32 s24, s46, s47
	s_add_i32 s52, 0, 0x14000
	ds_read_b128 v[142:145], v141
	ds_read_b128 v[146:149], v141 offset:1024
	ds_read_b128 v[150:153], v141 offset:2048
	ds_read_b128 v[154:157], v141 offset:3072
	v_add_u32_e32 v141, s52, v139
	ds_read_b128 v[158:161], v141
	ds_read_b128 v[162:165], v141 offset:1024
	ds_read_b128 v[166:169], v141 offset:2048
	ds_read_b128 v[170:173], v141 offset:3072
	v_lshl_add_u64 v[194:195], s[22:23], 0, v[136:137]
	s_add_i32 m0, s21, 0xc000
	ds_read_b128 v[174:177], v140
	ds_read_b128 v[178:181], v140 offset:1024
	ds_read_b128 v[182:185], v140 offset:2048
	ds_read_b128 v[186:189], v140 offset:3072
	ds_read_b128 v[190:193], v140 offset:4096
	ds_read_b128 v[208:211], v140 offset:5120
	ds_read_b128 v[212:215], v140 offset:6144
	ds_read_b128 v[216:219], v140 offset:7168
	global_load_lds_dwordx4 v[194:195], off
	v_lshl_add_u64 v[194:195], s[22:23], 0, v[134:135]
	s_add_i32 m0, s21, 0xe000
	s_nop 0
	global_load_lds_dwordx4 v[194:195], off
	s_waitcnt vmcnt(8)
	s_waitcnt lgkmcnt(0)
	v_mfma_f32_16x16x32_f16 v[128:131], v[142:145], v[174:177], v[128:131]
	v_mfma_f32_16x16x32_f16 v[120:123], v[150:153], v[174:177], v[120:123]
	v_mfma_f32_16x16x32_f16 v[112:115], v[142:145], v[182:185], v[112:115]
	v_mfma_f32_16x16x32_f16 v[104:107], v[150:153], v[182:185], v[104:107]
	s_barrier
	s_setprio 1
	v_mfma_f32_16x16x32_f16 v[96:99], v[142:145], v[190:193], v[96:99]
	v_mfma_f32_16x16x32_f16 v[88:91], v[150:153], v[190:193], v[88:91]
	v_mfma_f32_16x16x32_f16 v[80:83], v[142:145], v[212:215], v[80:83]
	v_mfma_f32_16x16x32_f16 v[72:75], v[150:153], v[212:215], v[72:75]
	v_mfma_f32_16x16x32_f16 v[128:131], v[146:149], v[178:181], v[128:131]
	v_mfma_f32_16x16x32_f16 v[120:123], v[154:157], v[178:181], v[120:123]
	v_mfma_f32_16x16x32_f16 v[112:115], v[146:149], v[186:189], v[112:115]
	v_mfma_f32_16x16x32_f16 v[104:107], v[154:157], v[186:189], v[104:107]
	v_mfma_f32_16x16x32_f16 v[96:99], v[146:149], v[208:211], v[96:99]
	v_mfma_f32_16x16x32_f16 v[88:91], v[154:157], v[208:211], v[88:91]
	v_mfma_f32_16x16x32_f16 v[80:83], v[146:149], v[216:219], v[80:83]
	v_mfma_f32_16x16x32_f16 v[72:75], v[154:157], v[216:219], v[72:75]
	v_mfma_f32_16x16x32_f16 v[124:127], v[158:161], v[174:177], v[124:127]
	v_mfma_f32_16x16x32_f16 v[116:119], v[166:169], v[174:177], v[116:119]
	v_mfma_f32_16x16x32_f16 v[108:111], v[158:161], v[182:185], v[108:111]
	v_mfma_f32_16x16x32_f16 v[100:103], v[166:169], v[182:185], v[100:103]
	v_mfma_f32_16x16x32_f16 v[92:95], v[158:161], v[190:193], v[92:95]
	v_mfma_f32_16x16x32_f16 v[84:87], v[166:169], v[190:193], v[84:87]
	v_mfma_f32_16x16x32_f16 v[76:79], v[158:161], v[212:215], v[76:79]
	v_mfma_f32_16x16x32_f16 v[68:71], v[166:169], v[212:215], v[68:71]
	v_mfma_f32_16x16x32_f16 v[124:127], v[162:165], v[178:181], v[124:127]
	v_mfma_f32_16x16x32_f16 v[116:119], v[170:173], v[178:181], v[116:119]
	v_mfma_f32_16x16x32_f16 v[108:111], v[162:165], v[186:189], v[108:111]
	v_mfma_f32_16x16x32_f16 v[100:103], v[170:173], v[186:189], v[100:103]
	v_mfma_f32_16x16x32_f16 v[92:95], v[162:165], v[208:211], v[92:95]
	v_mfma_f32_16x16x32_f16 v[84:87], v[170:173], v[208:211], v[84:87]
	v_mfma_f32_16x16x32_f16 v[76:79], v[162:165], v[216:219], v[76:79]
	v_mfma_f32_16x16x32_f16 v[68:71], v[170:173], v[216:219], v[68:71]
	s_setprio 0
	s_barrier
	s_add_i32 s50, s50, s36
	v_lshl_add_u64 v[194:195], s[24:25], 0, v[0:1]
	s_mov_b32 m0, s50
	ds_read_b128 v[174:177], v140 offset:16384
	ds_read_b128 v[178:181], v140 offset:17408
	ds_read_b128 v[182:185], v140 offset:18432
	ds_read_b128 v[186:189], v140 offset:19456
	ds_read_b128 v[190:193], v140 offset:20480
	ds_read_b128 v[208:211], v140 offset:21504
	ds_read_b128 v[212:215], v140 offset:22528
	ds_read_b128 v[216:219], v140 offset:23552
	global_load_lds_dwordx4 v[194:195], off
	s_add_i32 m0, s50, 0x2000
	s_add_u32 s50, s24, 0x20000
	v_lshl_add_u64 v[220:221], s[24:25], 0, v[132:133]
	s_addc_u32 s51, s25, 0
	s_add_i32 s52, s52, s36
	global_load_lds_dwordx4 v[220:221], off
	v_lshl_add_u64 v[222:223], s[50:51], 0, v[0:1]
	s_mov_b32 m0, s52
	v_lshl_add_u64 v[224:225], s[26:27], 0, v[132:133]
	global_load_lds_dwordx4 v[222:223], off
	v_lshl_add_u64 v[222:223], s[50:51], 0, v[132:133]
	s_add_i32 m0, s52, 0x2000
	s_nop 0
	global_load_lds_dwordx4 v[222:223], off
	v_lshl_add_u64 v[222:223], s[26:27], 0, v[0:1]
	s_mov_b32 m0, s21
	s_nop 0
	global_load_lds_dwordx4 v[222:223], off
	s_mov_b32 m0, s37
	s_nop 0
	global_load_lds_dwordx4 v[224:225], off
	s_waitcnt vmcnt(8)
	s_waitcnt lgkmcnt(0)
	v_mfma_f32_16x16x32_f16 v[64:67], v[142:145], v[174:177], v[64:67]
	v_mfma_f32_16x16x32_f16 v[56:59], v[150:153], v[174:177], v[56:59]
	v_mfma_f32_16x16x32_f16 v[48:51], v[142:145], v[182:185], v[48:51]
	v_mfma_f32_16x16x32_f16 v[40:43], v[150:153], v[182:185], v[40:43]
	s_barrier
; #define PG8_STAGE(bufoff, gbase, voff) do { _Pragma("unroll") for (int _i = 0; _i < 2; ++_i) \
;         __builtin_amdgcn_global_load_lds((const unsigned*)((const char*)(gbase) + (voff)[_i]), (LAS unsigned*)(lds + (bufoff) + ldsw + _i * 8192), 16, 0, 0); } while (0)
; #define PG8_LDA(dst, b, h) do { _Pragma("unroll") for (int m = 0; m < 4; ++m) _Pragma("unroll") for (int k = 0; k < 2; ++k) dst[m][k] = *(const LAS bf16x8*)(lds + PG8_SA(b, h) + aoff + m * 2048 + k * 1024); } while (0)
; #define PG8_LDB(dst, b, h) do { _Pragma("unroll") for (int n = 0; n < 2; ++n) _Pragma("unroll") for (int k = 0; k < 2; ++k) dst[n][k] = *(const LAS bf16x8*)(lds + PG8_SB(b, h) + boff + n * 2048 + k * 1024); } while (0)
; #define PG8_WAIT_V(n) asm volatile("s_waitcnt vmcnt(" #n ")" ::: "memory")
; #define PG8_WAIT_L(n) asm volatile("s_waitcnt lgkmcnt(" #n ")" ::: "memory")
; #define PG8_BAR __builtin_amdgcn_s_barrier()
; #define PG8_SCHED __builtin_amdgcn_sched_barrier(0)
; template <class Epi, class Sched, bool FUSED = false, bool APERM = false>
; __device__ __forceinline__ void gemm_phase(int wid_s, LAS unsigned char* lds, const Gemm g, const Sched& S, const Epi& E) {
;     ...
;             PG8_WAIT_V(8); PG8_WAIT_L(0); PG8_BAR; PG8_MMA(1, 0, At, B0); PG8_MMA(1, 1, At, B1); PG8_BAR; PG8_SCHED;
;             PG8_LDB(B0, 1, 0); PG8_LDB(B1, 1, 1); PG8_SCHED; PG8_LDA(At, 1, 0); PG8_STAGE(PG8_SA(0, 1), a2 + hstep, voffA);
;             PG8_WAIT_V(8); PG8_WAIT_L(0); PG8_BAR; PG8_MMA(0, 0, At, B0); PG8_MMA(0, 1, At, B1); PG8_BAR; PG8_SCHED;
	s_setprio 1
	v_mfma_f32_16x16x32_f16 v[32:35], v[142:145], v[190:193], v[32:35]
	v_mfma_f32_16x16x32_f16 v[24:27], v[150:153], v[190:193], v[24:27]
	v_mfma_f32_16x16x32_f16 v[16:19], v[142:145], v[212:215], v[16:19]
	v_mfma_f32_16x16x32_f16 v[8:11], v[150:153], v[212:215], v[8:11]
	v_mfma_f32_16x16x32_f16 v[64:67], v[146:149], v[178:181], v[64:67]
	v_mfma_f32_16x16x32_f16 v[56:59], v[154:157], v[178:181], v[56:59]
	v_mfma_f32_16x16x32_f16 v[48:51], v[146:149], v[186:189], v[48:51]
	v_mfma_f32_16x16x32_f16 v[40:43], v[154:157], v[186:189], v[40:43]
	v_mfma_f32_16x16x32_f16 v[32:35], v[146:149], v[208:211], v[32:35]
	v_mfma_f32_16x16x32_f16 v[24:27], v[154:157], v[208:211], v[24:27]
	v_mfma_f32_16x16x32_f16 v[16:19], v[146:149], v[216:219], v[16:19]
	v_mfma_f32_16x16x32_f16 v[8:11], v[154:157], v[216:219], v[8:11]
	v_mfma_f32_16x16x32_f16 v[60:63], v[158:161], v[174:177], v[60:63]
	v_mfma_f32_16x16x32_f16 v[52:55], v[166:169], v[174:177], v[52:55]
	v_mfma_f32_16x16x32_f16 v[44:47], v[158:161], v[182:185], v[44:47]
	v_mfma_f32_16x16x32_f16 v[36:39], v[166:169], v[182:185], v[36:39]
	v_mfma_f32_16x16x32_f16 v[28:31], v[158:161], v[190:193], v[28:31]
	v_mfma_f32_16x16x32_f16 v[20:23], v[166:169], v[190:193], v[20:23]
	v_mfma_f32_16x16x32_f16 v[12:15], v[158:161], v[212:215], v[12:15]
	v_mfma_f32_16x16x32_f16 v[4:7], v[166:169], v[212:215], v[4:7]
	v_mfma_f32_16x16x32_f16 v[60:63], v[162:165], v[178:181], v[60:63]
	v_mfma_f32_16x16x32_f16 v[52:55], v[170:173], v[178:181], v[52:55]
	v_mfma_f32_16x16x32_f16 v[44:47], v[162:165], v[186:189], v[44:47]
	v_mfma_f32_16x16x32_f16 v[36:39], v[170:173], v[186:189], v[36:39]
	v_mfma_f32_16x16x32_f16 v[28:31], v[162:165], v[208:211], v[28:31]
	v_mfma_f32_16x16x32_f16 v[20:23], v[170:173], v[208:211], v[20:23]
	v_mfma_f32_16x16x32_f16 v[12:15], v[162:165], v[216:219], v[12:15]
	v_mfma_f32_16x16x32_f16 v[4:7], v[170:173], v[216:219], v[4:7]
	s_setprio 0
	s_barrier
	s_add_i32 s50, 0, 0x18000
	v_add_u32_e32 v141, s50, v139
	s_add_i32 s51, 0, 0x1c000
	ds_read_b128 v[142:145], v141
	ds_read_b128 v[146:149], v141 offset:1024
	ds_read_b128 v[150:153], v141 offset:2048
	ds_read_b128 v[154:157], v141 offset:3072
	v_add_u32_e32 v141, s51, v139
	ds_read_b128 v[158:161], v141
	ds_read_b128 v[162:165], v141 offset:1024
	ds_read_b128 v[166:169], v141 offset:2048
	ds_read_b128 v[170:173], v141 offset:3072
	s_add_u32 s26, s26, 0x20000
	s_addc_u32 s27, s27, 0
	s_mov_b32 m0, s38
	v_lshl_add_u64 v[226:227], s[26:27], 0, v[0:1]
	ds_read_b128 v[174:177], v140 offset:32768
	ds_read_b128 v[178:181], v140 offset:33792
	ds_read_b128 v[182:185], v140 offset:34816
	ds_read_b128 v[186:189], v140 offset:35840
	ds_read_b128 v[190:193], v140 offset:36864
	ds_read_b128 v[208:211], v140 offset:37888
	ds_read_b128 v[212:215], v140 offset:38912
	ds_read_b128 v[216:219], v140 offset:39936
	global_load_lds_dwordx4 v[226:227], off
	v_lshl_add_u64 v[226:227], s[26:27], 0, v[132:133]
	s_mov_b32 m0, s39
	s_nop 0
	global_load_lds_dwordx4 v[226:227], off
	s_waitcnt vmcnt(8)
	s_waitcnt lgkmcnt(0)
	v_mfma_f32_16x16x32_f16 v[128:131], v[142:145], v[174:177], v[128:131]
	v_mfma_f32_16x16x32_f16 v[120:123], v[150:153], v[174:177], v[120:123]
	v_mfma_f32_16x16x32_f16 v[112:115], v[142:145], v[182:185], v[112:115]
	v_mfma_f32_16x16x32_f16 v[104:107], v[150:153], v[182:185], v[104:107]
	s_barrier
	s_setprio 1
	v_mfma_f32_16x16x32_f16 v[96:99], v[142:145], v[190:193], v[96:99]
	v_mfma_f32_16x16x32_f16 v[88:91], v[150:153], v[190:193], v[88:91]
	v_mfma_f32_16x16x32_f16 v[80:83], v[142:145], v[212:215], v[80:83]
	v_mfma_f32_16x16x32_f16 v[72:75], v[150:153], v[212:215], v[72:75]
	v_mfma_f32_16x16x32_f16 v[128:131], v[146:149], v[178:181], v[128:131]
	v_mfma_f32_16x16x32_f16 v[120:123], v[154:157], v[178:181], v[120:123]
	v_mfma_f32_16x16x32_f16 v[112:115], v[146:149], v[186:189], v[112:115]
	v_mfma_f32_16x16x32_f16 v[104:107], v[154:157], v[186:189], v[104:107]
	v_mfma_f32_16x16x32_f16 v[96:99], v[146:149], v[208:211], v[96:99]
	v_mfma_f32_16x16x32_f16 v[88:91], v[154:157], v[208:211], v[88:91]
	v_mfma_f32_16x16x32_f16 v[80:83], v[146:149], v[216:219], v[80:83]
	v_mfma_f32_16x16x32_f16 v[72:75], v[154:157], v[216:219], v[72:75]
	v_mfma_f32_16x16x32_f16 v[124:127], v[158:161], v[174:177], v[124:127]
	v_mfma_f32_16x16x32_f16 v[116:119], v[166:169], v[174:177], v[116:119]
	v_mfma_f32_16x16x32_f16 v[108:111], v[158:161], v[182:185], v[108:111]
	v_mfma_f32_16x16x32_f16 v[100:103], v[166:169], v[182:185], v[100:103]
	v_mfma_f32_16x16x32_f16 v[92:95], v[158:161], v[190:193], v[92:95]
	v_mfma_f32_16x16x32_f16 v[84:87], v[166:169], v[190:193], v[84:87]
	v_mfma_f32_16x16x32_f16 v[76:79], v[158:161], v[212:215], v[76:79]
	v_mfma_f32_16x16x32_f16 v[68:71], v[166:169], v[212:215], v[68:71]
	v_mfma_f32_16x16x32_f16 v[124:127], v[162:165], v[178:181], v[124:127]
	v_mfma_f32_16x16x32_f16 v[116:119], v[170:173], v[178:181], v[116:119]
	v_mfma_f32_16x16x32_f16 v[108:111], v[162:165], v[186:189], v[108:111]
	v_mfma_f32_16x16x32_f16 v[100:103], v[170:173], v[186:189], v[100:103]
	v_mfma_f32_16x16x32_f16 v[92:95], v[162:165], v[208:211], v[92:95]
	v_mfma_f32_16x16x32_f16 v[84:87], v[170:173], v[208:211], v[84:87]
	v_mfma_f32_16x16x32_f16 v[76:79], v[162:165], v[216:219], v[76:79]
	v_mfma_f32_16x16x32_f16 v[68:71], v[170:173], v[216:219], v[68:71]
	s_setprio 0
	s_barrier
; #define PG8_STAGE(bufoff, gbase, voff) do { _Pragma("unroll") for (int _i = 0; _i < 2; ++_i) \
;         __builtin_amdgcn_global_load_lds((const unsigned*)((const char*)(gbase) + (voff)[_i]), (LAS unsigned*)(lds + (bufoff) + ldsw + _i * 8192), 16, 0, 0); } while (0)
; #define PG8_LDA(dst, b, h) do { _Pragma("unroll") for (int m = 0; m < 4; ++m) _Pragma("unroll") for (int k = 0; k < 2; ++k) dst[m][k] = *(const LAS bf16x8*)(lds + PG8_SA(b, h) + aoff + m * 2048 + k * 1024); } while (0)
; #define PG8_WAIT_V(n) asm volatile("s_waitcnt vmcnt(" #n ")" ::: "memory")
; #define PG8_WAIT_L(n) asm volatile("s_waitcnt lgkmcnt(" #n ")" ::: "memory")
; #define PG8_BAR __builtin_amdgcn_s_barrier()
; #define PG8_SCHED __builtin_amdgcn_sched_barrier(0)
; template <class Epi, class Sched, bool FUSED = false, bool APERM = false>
; __device__ __forceinline__ void gemm_phase(int wid_s, LAS unsigned char* lds, const Gemm g, const Sched& S, const Epi& E) {
;     ...
;             PG8_LDA(At, 1, 1); PG8_STAGE(PG8_SB(1, 0), b3, voffB); PG8_STAGE(PG8_SB(1, 1), b3 + hstep, voffB); PG8_STAGE(PG8_SA(1, 0), a3, voffA);
;             PG8_WAIT_V(8); PG8_WAIT_L(0); PG8_BAR; PG8_MMA(1, 0, At, B0); PG8_MMA(1, 1, At, B1); PG8_BAR; PG8_SCHED;
;         }
;         if (wr == 0) PG8_BAR;
	s_add_i32 s26, s50, s36
	v_lshl_add_u64 v[194:195], v[194:195], 0, s[12:13]
	s_mov_b32 m0, s26
	ds_read_b128 v[174:177], v140 offset:49152
	ds_read_b128 v[178:181], v140 offset:50176
	ds_read_b128 v[182:185], v140 offset:51200
	ds_read_b128 v[186:189], v140 offset:52224
	ds_read_b128 v[190:193], v140 offset:53248
	ds_read_b128 v[208:211], v140 offset:54272
	ds_read_b128 v[212:215], v140 offset:55296
	ds_read_b128 v[216:219], v140 offset:56320
	global_load_lds_dwordx4 v[194:195], off
	s_add_i32 m0, s26, 0x2000
	s_add_u32 s24, s24, 0x20080
	v_lshl_add_u64 v[194:195], v[220:221], 0, s[12:13]
	s_addc_u32 s25, s25, 0
	s_add_i32 s26, s51, s36
	global_load_lds_dwordx4 v[194:195], off
	v_lshl_add_u64 v[194:195], s[24:25], 0, v[0:1]
	s_mov_b32 m0, s26
	s_nop 0
	global_load_lds_dwordx4 v[194:195], off
	v_lshl_add_u64 v[194:195], s[24:25], 0, v[132:133]
	s_add_i32 m0, s26, 0x2000
	s_nop 0
	global_load_lds_dwordx4 v[194:195], off
	v_lshl_add_u64 v[194:195], v[222:223], 0, s[12:13]
	s_mov_b32 m0, s41
	s_nop 0
	global_load_lds_dwordx4 v[194:195], off
	v_lshl_add_u64 v[194:195], v[224:225], 0, s[12:13]
	s_mov_b32 m0, s42
	s_nop 0
	global_load_lds_dwordx4 v[194:195], off
	s_waitcnt vmcnt(8)
	s_waitcnt lgkmcnt(0)
	v_mfma_f32_16x16x32_f16 v[64:67], v[142:145], v[174:177], v[64:67]
	v_mfma_f32_16x16x32_f16 v[56:59], v[150:153], v[174:177], v[56:59]
	v_mfma_f32_16x16x32_f16 v[48:51], v[142:145], v[182:185], v[48:51]
	v_mfma_f32_16x16x32_f16 v[40:43], v[150:153], v[182:185], v[40:43]
	s_barrier
	s_setprio 1
	v_mfma_f32_16x16x32_f16 v[32:35], v[142:145], v[190:193], v[32:35]
	v_mfma_f32_16x16x32_f16 v[24:27], v[150:153], v[190:193], v[24:27]
	v_mfma_f32_16x16x32_f16 v[16:19], v[142:145], v[212:215], v[16:19]
	v_mfma_f32_16x16x32_f16 v[8:11], v[150:153], v[212:215], v[8:11]
	v_mfma_f32_16x16x32_f16 v[64:67], v[146:149], v[178:181], v[64:67]
	v_mfma_f32_16x16x32_f16 v[56:59], v[154:157], v[178:181], v[56:59]
	v_mfma_f32_16x16x32_f16 v[48:51], v[146:149], v[186:189], v[48:51]
	v_mfma_f32_16x16x32_f16 v[40:43], v[154:157], v[186:189], v[40:43]
	v_mfma_f32_16x16x32_f16 v[32:35], v[146:149], v[208:211], v[32:35]
	v_mfma_f32_16x16x32_f16 v[24:27], v[154:157], v[208:211], v[24:27]
	v_mfma_f32_16x16x32_f16 v[16:19], v[146:149], v[216:219], v[16:19]
	v_mfma_f32_16x16x32_f16 v[8:11], v[154:157], v[216:219], v[8:11]
	v_mfma_f32_16x16x32_f16 v[60:63], v[158:161], v[174:177], v[60:63]
	v_mfma_f32_16x16x32_f16 v[52:55], v[166:169], v[174:177], v[52:55]
	v_mfma_f32_16x16x32_f16 v[44:47], v[158:161], v[182:185], v[44:47]
	v_mfma_f32_16x16x32_f16 v[36:39], v[166:169], v[182:185], v[36:39]
	v_mfma_f32_16x16x32_f16 v[28:31], v[158:161], v[190:193], v[28:31]
	v_mfma_f32_16x16x32_f16 v[20:23], v[166:169], v[190:193], v[20:23]
	v_mfma_f32_16x16x32_f16 v[12:15], v[158:161], v[212:215], v[12:15]
	v_mfma_f32_16x16x32_f16 v[4:7], v[166:169], v[212:215], v[4:7]
	v_mfma_f32_16x16x32_f16 v[60:63], v[162:165], v[178:181], v[60:63]
	v_mfma_f32_16x16x32_f16 v[52:55], v[170:173], v[178:181], v[52:55]
	v_mfma_f32_16x16x32_f16 v[44:47], v[162:165], v[186:189], v[44:47]
	v_mfma_f32_16x16x32_f16 v[36:39], v[170:173], v[186:189], v[36:39]
	v_mfma_f32_16x16x32_f16 v[28:31], v[162:165], v[208:211], v[28:31]
	v_mfma_f32_16x16x32_f16 v[20:23], v[170:173], v[208:211], v[20:23]
	v_mfma_f32_16x16x32_f16 v[12:15], v[162:165], v[216:219], v[12:15]
	v_mfma_f32_16x16x32_f16 v[4:7], v[170:173], v[216:219], v[4:7]
	s_setprio 0
	s_barrier
	s_add_i32 s49, s49, 2
	s_add_u32 s47, s47, 0x100
	s_addc_u32 s48, s48, 0
	s_add_u32 s22, s22, 0x100
	s_addc_u32 s23, s23, 0
	s_cmp_gt_u32 s49, 5
	s_cbranch_scc0 .LBB0_582
	s_and_b64 vcc, exec, s[6:7]
	s_cbranch_vccz .LBB0_585
	s_barrier
